# own block tile fetched HBM->LDS during the selected stream's last stage into the idle stage buffer (own-block step skips its load, ds_write pair and barrier); on top of v36
# baseline (speedup 1.0000x reference)
; #define LAS __attribute__((address_space(3)))
; __device__ __forceinline__ int launder_v(int x) { asm volatile("" : "+v"(x)); return x; }
; __device__ __forceinline__ void nsa_block_task(Ctx& C, int task, bf16* ONSA_OUT) {
;     ...
;     LAS unsigned* ANYM = (LAS unsigned*)(C.lds + 135168 + w * 64);
;     { const int la = launder_v(lane); if (la < 16) { const int cgx = la >> 3, w8 = la & 7; ANYM[la] = SELM[(4 * cgx + 0) * 8 + w8] | SELM[(4 * cgx + 1) * 8 + w8] | SELM[(4 * cgx + 2) * 8 + w8] | SELM[(4 * cgx + 3) * 8 + w8]; } }
.LBB0_1204:
	s_mov_b32 s42, 0
	s_mov_b32 s43, 0
	s_waitcnt lgkmcnt(0)
	v_mov_b32_e32 v0, v190
	s_nop 0
	v_cmp_gt_i32_e32 vcc, 16, v0
	s_and_saveexec_b64 s[16:17], vcc
	s_cbranch_execz .LBB0_1206
	v_lshlrev_b32_e32 v2, 4, v0
	v_lshlrev_b32_e32 v0, 2, v0
	v_and_b32_e32 v52, 0xffffff80, v2
	v_and_b32_e32 v53, 28, v0
	v_add3_u32 v54, s76, v52, v53
	v_or_b32_e32 v52, v52, v53
	ds_read2_b32 v[2:3], v54 offset1:8
	v_add_u32_e32 v52, s76, v52
	ds_read_b32 v53, v54 offset:64
	ds_read_b32 v52, v52 offset:96
	v_add_u32_e32 v0, s77, v0
	s_waitcnt lgkmcnt(2)
	v_or_b32_e32 v2, v3, v2
	s_waitcnt lgkmcnt(0)
	v_or3_b32 v2, v2, v53, v52
	ds_write_b32 v0, v2

; #define LAS __attribute__((address_space(3)))
; __device__ __forceinline__ int launder_v(int x) { asm volatile("" : "+v"(x)); return x; }
; template <int STG, class F>
; __device__ __forceinline__ void stream_tiles(Ctx& C, const TileSrc& src, int tile0, int ntiles, LAS unsigned char* bufs, F&& compute) {
;     ...
;     for (int st = 0; st < nst; ++st) {
;         const int tidl = launder_v(C.tid);
;         const bool more = st + 1 < nst;
;         if (more) {
; #pragma unroll
;             for (int h = 0; h < STG; ++h) { const int t = tile0 + STG * (st + 1) + h; tile_fetch(src, 64 * (t < tlast ? t : tlast), tidl, rk[h], rv[h]); } }
;         LAS unsigned char* cur = bufs + (st & 1) * (STG * 16384);
; #pragma unroll 1
;         for (int h = 0; h < STG; ++h) if (STG * st + h < ntiles) compute(cur + h * 16384, tile0 + STG * st + h);
;         if (more) {
; #pragma unroll
;             for (int h = 0; h < STG; ++h) tile_store(bufs + ((st + 1) & 1) * (STG * 16384) + h * 16384, tidl, rk[h], rv[h]); }
;         __syncthreads();
; __device__ __forceinline__ void nsa_block_task(Ctx& C, int task, bf16* ONSA_OUT) {
;     ...
;         stream_tiles<1>(C, src, qb, 1, bufs, [&](const LAS unsigned char* buf, int j) {
.Lown_pf:
	s_lshl_b32 s25, s34, 16
	s_and_b32 s25, s25, 0x10000
	s_add_i32 s45, s25, s44
	s_add_i32 m0, s45, 0x0
	s_lshl_b32 s98, s94, 13
	s_add_u32 s98, s18, s98
	s_addc_u32 s99, s19, 0
	global_load_lds_dwordx4 v185, s[98:99]
	s_add_i32 m0, s45, 0x2000
	s_lshl_b32 s100, s94, 7
	s_add_u32 s100, s16, s100
	s_addc_u32 s101, s17, 0
	global_load_lds_dwordx4 v198, s[100:101]
	s_mov_b32 s42, s25
	s_mov_b32 s43, 1
	s_branch .LBB0_1210
.LBB0_1225:
	s_waitcnt vmcnt(0)
.LBB0_1227:
	s_add_i32 s28, s28, 4
	s_add_i32 s27, s27, 4
	s_add_i32 s26, s26, 0x10000
	s_cmp_lg_u32 s34, s29
	s_waitcnt lgkmcnt(0)
	s_barrier
	s_cbranch_scc0 .LBB0_1230
	s_mov_b32 s23, s34
	s_branch .LBB0_1208

; #define LAS __attribute__((address_space(3)))
; __device__ __forceinline__ float fexp2(float x) { return __builtin_amdgcn_exp2f(x); }
; __device__ __forceinline__ int launder_v(int x) { asm volatile("" : "+v"(x)); return x; }
; template <class Mask>
; __device__ __forceinline__ void attn_tile64(AttnAcc& a, const bf16x8 (&kf)[2][2][2], const bf16x8 (&vf)[2][4], const bf16x8 (&bq)[2], int kb, int fq, const Mask& mask) {
;     f4 s[2][2];
; #pragma unroll
;     for (int ch = 0; ch < 2; ++ch) qk_scores(kf[ch], bq, s[ch][0], s[ch][1]);
;     bool v[2][2][4]; float mx = -1e30f;
; #pragma unroll
;     for (int ch = 0; ch < 2; ++ch)
; #pragma unroll
;         for (int h = 0; h < 2; ++h)
; #pragma unroll
;             for (int j = 0; j < 4; ++j) { v[ch][h][j] = mask(kb + 32 * ch + 8 * fq + 4 * h + j); mx = fmaxf(mx, v[ch][h][j] ? s[ch][h][j] : -1e30f); }
;     if (__any(mx > a.m + MAX_SLACK)) {
;         mx = fmaxf(mx, __shfl_xor(mx, 16)); mx = fmaxf(mx, __shfl_xor(mx, 32));
;         const float mn = fmaxf(a.m, mx), alpha = fexp2(a.m - mn); a.m = mn; a.l *= alpha;
; #pragma unroll
;         for (int c = 0; c < 4; ++c) a.o[c] = a.o[c] * alpha;
;     }
; __device__ __forceinline__ void nsa_block_task(Ctx& C, int task, bf16* ONSA_OUT) {
;     ...
;         stream_tiles<1>(C, src, qb, 1, bufs, [&](const LAS unsigned char* buf, int j) {
;             bf16x8 kf[2][2][2], vf[2][4]; { const int ll = launder_v(lane);
; #pragma unroll
;                 for (int ch = 0; ch < 2; ++ch) { tile_read_k(buf, ch, ll, kf[ch]); tile_read_v(buf, ch, ll, vf[ch]); } }
; #pragma unroll
;             for (int cg = 0; cg < 2; ++cg) { const int tq = tl[cg];
;                 attn_tile64(a[cg], kf, vf, bq[cg], 64 * j, fq, [&](int key) { return key <= tq; }); }
.LBB0_1230:
	v_mov_b32_e32 v37, v189
	v_mov_b64_e32 v[38:39], s[16:17]
	s_waitcnt vmcnt(0)
	v_ashrrev_i32_e32 v64, 3, v37
	v_add_u32_e32 v2, s54, v64
	v_ashrrev_i32_e32 v3, 31, v2
	v_lshlrev_b64 v[2:3], 7, v[2:3]
	v_lshlrev_b32_e32 v65, 4, v37
	v_lshl_add_u64 v[2:3], s[18:19], 0, v[2:3]
	v_and_b32_e32 v0, 0x70, v65
	v_mad_i64_i32 v[38:39], s[16:17], v64, s92, v[38:39]
	s_mov_b32 s55, s51
	v_lshl_add_u64 v[2:3], v[2:3], 0, v[0:1]
	v_lshl_add_u64 v[38:39], s[54:55], 1, v[38:39]
	v_lshl_add_u64 v[38:39], v[38:39], 0, v[0:1]
	s_cmp_lg_u32 s43, 0
	s_cbranch_scc1 .Lown_noload
	global_load_dwordx4 v[56:59], v[2:3], off
	global_load_dwordx4 v[60:63], v[38:39], off
.Lown_noload:
	v_lshlrev_b32_e32 v3, 2, v64
	v_lshrrev_b32_e32 v38, 1, v64
	v_and_b32_e32 v39, 35, v64
	v_and_b32_e32 v3, 16, v3
	v_and_b32_e32 v38, 12, v38
	v_or3_b32 v3, v3, v39, v38
	v_lshlrev_b32_e32 v38, 7, v3
	v_lshrrev_b32_e32 v3, 1, v3
	v_xor_b32_e32 v3, v3, v37
	v_lshlrev_b32_e32 v3, 4, v3
	v_and_b32_e32 v3, 0x70, v3
	v_mov_b32_e32 v0, v189
	v_lshlrev_b32_e32 v64, 7, v64
	v_bitop3_b32 v65, v65, s91, v37 bitop3:0x48
	v_add3_u32 v3, 0, v38, v3
	v_mov_b32_e32 v2, v190
	v_add3_u32 v64, 0, v64, v65
	v_add_u32_e32 v136, s54, v192
	v_cmp_lt_i32_e64 s[44:45], v136, v216
	v_cmp_gt_i32_e64 s[16:17], v136, v216
	v_or_b32_e32 v142, 4, v136
	v_or_b32_e32 v137, 7, v136
	v_cmp_gt_i32_e64 s[46:47], v142, v216
	v_add_u32_e32 v138, 32, v136
	v_add_u32_e32 v139, 33, v136
	v_cmp_gt_i32_e64 s[40:41], v137, v216
	v_add_u32_e32 v140, 34, v136
	v_add_u32_e32 v141, 35, v136
	v_cmp_gt_i32_e64 s[28:29], v138, v216
	v_cmp_gt_i32_e64 s[24:25], v139, v216
	v_cmp_gt_i32_e64 s[26:27], v140, v216
	v_cmp_gt_i32_e64 s[18:19], v141, v216
	s_waitcnt vmcnt(0) lgkmcnt(0)
	s_cmp_lg_u32 s43, 0
	s_cbranch_scc1 .Lown_nowrite
	ds_write_b128 v3, v[56:59]
	ds_write_b128 v64, v[60:63] offset:8192
	s_waitcnt lgkmcnt(0)
	s_barrier
.Lown_nowrite:
	v_or_b32_e32 v3, 5, v136
	v_lshlrev_b32_e32 v0, 7, v2
	v_ashrrev_i32_e32 v37, 4, v2
	v_lshrrev_b32_e32 v38, 1, v2
	v_and_b32_e32 v0, 0x780, v0
	v_bitop3_b32 v2, v38, v37, 7 bitop3:0x6c
	v_add_u32_e32 v39, s42, v0
	v_lshl_add_u32 v68, v2, 4, v39
	ds_read_b128 v[88:91], v68
	ds_read_b128 v[92:95], v68 offset:2048
	v_add_u32_e32 v37, 4, v37
	v_bitop3_b32 v37, v37, v38, 7 bitop3:0x78
	v_lshl_add_u32 v38, v37, 4, v39
	ds_read_b128 v[96:99], v68 offset:4096
	ds_read_b128 v[100:103], v68 offset:6144
	ds_read_b128 v[104:107], v38
	ds_read_b128 v[108:111], v38 offset:2048
	ds_read_b128 v[112:115], v38 offset:4096
	ds_read_b128 v[116:119], v38 offset:6144
	s_waitcnt lgkmcnt(7)
	v_mfma_f32_16x16x32_bf16 v[56:59], v[88:91], v[4:7], 0
	ds_read_b128 v[84:87], v68 offset:8192
	ds_read_b128 v[80:83], v68 offset:10240
	ds_read_b128 v[76:79], v68 offset:12288
	ds_read_b128 v[72:75], v68 offset:14336
	v_or_b32_e32 v0, 2, v136
	v_or_b32_e32 v2, 3, v136
	s_waitcnt lgkmcnt(10)
	v_mfma_f32_16x16x32_bf16 v[60:63], v[92:95], v[4:7], 0
	v_cmp_gt_i32_e64 s[30:31], v0, v216
	v_cmp_gt_i32_e64 s[34:35], v2, v216
	v_or_b32_e32 v37, 6, v136
	s_waitcnt lgkmcnt(9)
	v_mfma_f32_16x16x32_bf16 v[64:67], v[96:99], v[4:7], 0
	v_cmp_gt_i32_e64 s[48:49], v3, v216
	v_cmp_gt_i32_e64 s[38:39], v37, v216
	s_waitcnt lgkmcnt(7)
	v_mfma_f32_16x16x32_bf16 v[128:131], v[104:107], v[8:11], v[56:59]
	v_mfma_f32_16x16x32_bf16 v[124:127], v[100:103], v[4:7], 0
	s_waitcnt lgkmcnt(6)
	v_mfma_f32_16x16x32_bf16 v[132:135], v[108:111], v[8:11], v[60:63]
	s_nop 4
	v_cndmask_b32_e64 v39, v232, v129, s[44:45]
	v_max_f32_e32 v39, v39, v39
	v_cndmask_b32_e64 v143, v130, v232, s[30:31]
	s_waitcnt lgkmcnt(5)
	v_mfma_f32_16x16x32_bf16 v[120:123], v[112:115], v[8:11], v[64:67]
	ds_read_b128 v[68:71], v38 offset:8192
	s_nop 1
	ds_read_b128 v[64:67], v38 offset:10240
	ds_read_b128 v[60:63], v38 offset:12288
	ds_read_b128 v[56:59], v38 offset:14336
	v_max_f32_e32 v38, v128, v128
	v_max_f32_e32 v38, 0xf149f2ca, v38
	v_cndmask_b32_e64 v38, v38, v232, s[16:17]
	v_cndmask_b32_e64 v144, v131, v232, s[34:35]
	v_max_f32_e32 v38, v38, v39
	s_waitcnt lgkmcnt(8)
	v_mfma_f32_16x16x32_bf16 v[124:127], v[116:119], v[8:11], v[124:127]
	v_cndmask_b32_e64 v142, v132, v232, s[46:47]
	v_cndmask_b32_e64 v145, v133, v232, s[48:49]
	v_max3_f32 v38, v38, v143, v144
	v_cndmask_b32_e64 v146, v134, v232, s[38:39]
	v_cndmask_b32_e64 v147, v135, v232, s[40:41]
	v_max3_f32 v38, v38, v142, v145
	v_cndmask_b32_e64 v148, v120, v232, s[28:29]
	v_cndmask_b32_e64 v149, v121, v232, s[24:25]
	v_max3_f32 v38, v38, v146, v147
	v_add_u32_e32 v142, 36, v136
	v_add_u32_e32 v143, 37, v136
	v_cndmask_b32_e64 v150, v122, v232, s[26:27]
	v_max3_f32 v38, v38, v148, v149
	v_cndmask_b32_e64 v39, v123, v232, s[18:19]
	v_cmp_gt_i32_e64 s[36:37], v142, v216
	v_cmp_gt_i32_e64 s[42:43], v143, v216
	v_max3_f32 v38, v38, v150, v39
	v_cndmask_b32_e64 v39, v124, v232, s[36:37]
	v_cndmask_b32_e64 v144, v125, v232, s[42:43]
	v_max3_f32 v38, v38, v39, v144
	v_add_u32_e32 v144, 38, v136
	v_add_u32_e32 v145, 39, v136
	v_cmp_gt_i32_e64 s[20:21], v144, v216
	v_cmp_gt_i32_e64 s[22:23], v145, v216
	s_nop 0
	v_cndmask_b32_e64 v39, v126, v232, s[20:21]
	v_cndmask_b32_e64 v146, v127, v232, s[22:23]
	v_max3_f32 v38, v38, v39, v146
	v_add_f32_e32 v39, 0x41000000, v170
	v_cmp_gt_f32_e32 vcc, v38, v39
	s_cbranch_vccz .LBB0_1232
	ds_bpermute_b32 v39, v217, v38
	v_max_f32_e32 v38, v38, v38
	s_waitcnt lgkmcnt(0)
	v_max_f32_e32 v39, v39, v39
	v_max_f32_e32 v38, v38, v39
	ds_bpermute_b32 v39, v219, v38
	s_waitcnt lgkmcnt(0)
	v_max3_f32 v39, v170, v38, v39
	v_sub_f32_e32 v38, v170, v39
	v_exp_f32_e32 v38, v38
	v_mov_b32_e32 v170, v39
	v_mul_f32_e32 v36, v36, v38
	v_pk_mul_f32 v[54:55], v[54:55], v[38:39] op_sel_hi:[1,0]
	v_pk_mul_f32 v[52:53], v[52:53], v[38:39] op_sel_hi:[1,0]
	v_pk_mul_f32 v[50:51], v[50:51], v[38:39] op_sel_hi:[1,0]
	v_pk_mul_f32 v[48:49], v[48:49], v[38:39] op_sel_hi:[1,0]
	v_pk_mul_f32 v[46:47], v[46:47], v[38:39] op_sel_hi:[1,0]
	v_pk_mul_f32 v[44:45], v[44:45], v[38:39] op_sel_hi:[1,0]
	v_pk_mul_f32 v[42:43], v[42:43], v[38:39] op_sel_hi:[1,0]
	v_pk_mul_f32 v[40:41], v[40:41], v[38:39] op_sel_hi:[1,0]
